# sel: unit-end barriers merged; half-1 tile prefetch; queue result parked in SGPR
# baseline (speedup 1.0000x reference)
.LBB0_1141:
	s_waitcnt lgkmcnt(0)
	s_add_i32 s6, s18, s12
	v_lshl_add_u32 v0, v96, 2, s40
	s_ashr_i32 s7, s6, 31
	ds_read_b128 v[0:3], v0
	s_lshl_b64 s[6:7], s[6:7], 10
	s_add_u32 s6, s24, s6
	s_addc_u32 s7, s25, s7
	v_lshl_add_u64 v[4:5], v[96:97], 2, s[6:7]
	s_waitcnt lgkmcnt(0)
	global_store_dwordx4 v[4:5], v[0:3], off
	s_and_saveexec_b64 s[6:7], s[28:29]
	s_cbranch_execz .LBB0_808
	v_mov_b32_e32 v0, s3
	v_mov_b32_e32 v105, s101
	ds_write_b32 v0, v105
	s_branch .LBB0_808
